# baseline (speedup 1.0000x reference)
; #define PAIR_LOOP(N) for (int pi_ = blockIdx.x; 2 * pi_ < (N); pi_ += gridDim.x)
; __global__ void __launch_bounds__(512, 2) fwd_megakernel(Params p) {
;     ...
;         PAIR_LOOP(576 * 4) { const int it = 2 * pi_ + half; cmlp_item(p, j, it >> 2, it & 3, ZB, (u16*)hsm); }
.LBB0_1552:
	v_xor_b32_e32 v0, 1, v197
	v_cmp_lt_i32_e32 vcc, v0, v198
	v_readlane_b32 s44, v254, 44
	v_readlane_b32 s0, v255, 10
	v_cndmask_b32_e32 v0, v197, v0, vcc
	v_lshlrev_b32_e32 v71, 2, v0
	v_readlane_b32 s1, v255, 17
	v_readlane_b32 s8, v254, 0
	v_readlane_b32 s46, v254, 46
	v_readlane_b32 s47, v254, 47
	v_readlane_b32 s48, v254, 48
	v_readlane_b32 s49, v254, 49
	v_readlane_b32 s11, v255, 18
	v_readlane_b32 s45, v254, 45
	v_readlane_b32 s50, v254, 50
	v_readlane_b32 s51, v254, 51
	s_sub_i32 s6, s87, s8
	s_add_i32 s6, s6, -1
	s_sub_i32 s7, s6, s8
	s_lshl_b32 s7, s7, 1
	s_add_i32 s0, s0, s7
	s_lshl_b32 s7, s7, 5
	s_add_i32 s1, s1, s7
	s_mov_b32 s8, s6
